# attention loop: next mask word loaded straight into its register, back-edge vmcnt(0) wait and two copies removed (loads keep a full tile pair in flight)
# baseline (speedup 1.0000x reference)
; __device__ __forceinline__ void attn_unit(const AttArgs& a, int b, int h, int qb, LAS unsigned char* shm, int tid) {
;     ...
;         { typedef float f32x2_t __attribute__((ext_vector_type(2))); f32x2_t rs2 = {0.f, 0.f};
; #pragma unroll
;           for (int r = 0; r < 16; ++r) { p0[r] = __builtin_amdgcn_exp2f(p0[r]); p1[r] = __builtin_amdgcn_exp2f(p1[r]); rs2 += (f32x2_t){p0[r], p1[r]}; }
;           rs = rs2[0] + rs2[1]; l_run += rs; }
;         const bool regrow = __any(rs > 1.0995e12f);
;         u32x4_t pw0, pw1, pw2, pw3;
;         pw0 = (u32x4_t){cvtpk(p0[0], p0[1]), cvtpk(p0[2], p0[3]), cvtpk(p0[4], p0[5]), cvtpk(p0[6], p0[7])}; pw1 = (u32x4_t){cvtpk(p0[8], p0[9]), cvtpk(p0[10], p0[11]), cvtpk(p0[12], p0[13]), cvtpk(p0[14], p0[15])};
;         pw2 = (u32x4_t){cvtpk(p1[0], p1[1]), cvtpk(p1[2], p1[3]), cvtpk(p1[4], p1[5]), cvtpk(p1[6], p1[7])}; pw3 = (u32x4_t){cvtpk(p1[8], p1[9]), cvtpk(p1[10], p1[11]), cvtpk(p1[12], p1[13]), cvtpk(p1[14], p1[15])};
.Latt_j0:
	v_cvt_pk_bf16_f32 v196, v34, v35
	v_pk_add_f32 v[212:213], v[34:35], v[36:37]
	v_cvt_pk_bf16_f32 v197, v36, v37
	v_pk_add_f32 v[212:213], v[38:39], v[212:213]
	v_cvt_pk_bf16_f32 v198, v38, v39
	v_pk_add_f32 v[212:213], v[40:41], v[212:213]
	v_cvt_pk_bf16_f32 v199, v40, v41
	v_pk_add_f32 v[212:213], v[42:43], v[212:213]
	v_cvt_pk_bf16_f32 v200, v42, v43
	v_pk_add_f32 v[212:213], v[44:45], v[212:213]
	v_cvt_pk_bf16_f32 v201, v44, v45
	v_pk_add_f32 v[212:213], v[46:47], v[212:213]
	v_cvt_pk_bf16_f32 v202, v46, v47
	v_pk_add_f32 v[212:213], v[48:49], v[212:213]
	v_cvt_pk_bf16_f32 v203, v48, v49
	s_waitcnt lgkmcnt(0)
	s_andn2_b64 vcc, exec, s[16:17]
	s_cbranch_vccnz .Latt_w0
	s_waitcnt vmcnt(3)
	s_branch .Latt_w1

; __device__ __forceinline__ void attn_unit(const AttArgs& a, int b, int h, int qb, LAS unsigned char* shm, int tid) {
;     ...
;         if (t + 2 < NT) { kr[par] = *(const u32x4_t*)(ksrc + (size_t)(t + 2) * 64 * 256); vr[par] = *(const u32x4_t*)(vsrc + (size_t)(t + 2) * 64 * 256); mwr[par] = mrow[(size_t)(t + 2) * SEQ]; }
;         f32x16 p0, p1;
;         { const unsigned nm0 = ~((unsigned)mw >> (4 * hi)), nm1 = ~((unsigned)(mw >> 32) >> (4 * hi)), nb = __float_as_uint(-m_run);
; #pragma unroll
;           for (int r = 0; r < 16; ++r) { const int bit = (r & 3) + 8 * (r >> 2); const unsigned t0 = (unsigned)__builtin_amdgcn_sbfe((int)nm0, bit, 1), t1 = (unsigned)__builtin_amdgcn_sbfe((int)nm1, bit, 1);
;               p0[r] = __uint_as_float((t0 & 0xff800000u) | (~t0 & nb)); p1[r] = __uint_as_float((t1 & 0xff800000u) | (~t1 & nb)); } }
;         { LAS unsigned char* kb = Kb + hi * 1024 + r32 * 16;
; #pragma unroll
;           for (int d0 = 0; d0 < 4; ++d0) { const bf16x8 k0 = *(const LAS bf16x8*)(kb + d0 * 2048), k1 = *(const LAS bf16x8*)(kb + d0 * 2048 + 512);
;               p0 = __builtin_amdgcn_mfma_f32_32x32x16_bf16(k0, qr[d0], p0, 0, 0, 0); p1 = __builtin_amdgcn_mfma_f32_32x32x16_bf16(k1, qr[d0], p1, 0, 0, 0); } }
;         if (t == 0) {
;             float rm = __builtin_amdgcn_fmed3f(p0[0], p1[0], BIGF);
; #pragma unroll
;             for (int r = 1; r < 16; ++r) rm = __builtin_amdgcn_fmed3f(rm, __builtin_amdgcn_fmed3f(p0[r], p1[r], BIGF), BIGF);
;             const float rmf = __builtin_amdgcn_fmed3f(rm, __shfl_xor(rm, 32), BIGF); const float dl = (rmf == -INFINITY) ? 0.f : rmf;
;             m_run += dl;
; #pragma unroll
;             for (int r = 0; r < 16; ++r) { p0[r] -= dl; p1[r] -= dl; } }
;         float rs;
;         { typedef float f32x2_t __attribute__((ext_vector_type(2))); f32x2_t rs2 = {0.f, 0.f};
; #pragma unroll
;           for (int r = 0; r < 16; ++r) { p0[r] = __builtin_amdgcn_exp2f(p0[r]); p1[r] = __builtin_amdgcn_exp2f(p1[r]); rs2 += (f32x2_t){p0[r], p1[r]}; }
;           rs = rs2[0] + rs2[1]; l_run += rs; }
;         const bool regrow = __any(rs > 1.0995e12f);
;         u32x4_t pw0, pw1, pw2, pw3;
;         pw0 = (u32x4_t){cvtpk(p0[0], p0[1]), cvtpk(p0[2], p0[3]), cvtpk(p0[4], p0[5]), cvtpk(p0[6], p0[7])}; pw1 = (u32x4_t){cvtpk(p0[8], p0[9]), cvtpk(p0[10], p0[11]), cvtpk(p0[12], p0[13]), cvtpk(p0[14], p0[15])};
.Latt_w1:
	ds_write_b128 v117, v[90:93] offset:16384
	ds_write_b128 v117, v[94:97] offset:24576
	v_mfma_f32_32x32x16_bf16 v[2:17], v[196:199], v[178:181], v[2:17]
	ds_read_b64_tr_b16 v[178:179],v153 offset:2048
	ds_read_b64_tr_b16 v[180:181],v153 offset:2560
	v_exp_f32_e32 v50, v50
	v_exp_f32_e32 v51, v51
	v_exp_f32_e32 v52, v52
	v_exp_f32_e32 v53, v53
	v_mfma_f32_32x32x16_bf16 v[18:33], v[196:199], v[182:185], v[18:33]
	ds_read_b64_tr_b16 v[182:183],v153 offset:6144
	ds_read_b64_tr_b16 v[184:185],v153 offset:6656
	v_exp_f32_e32 v54, v54
	v_exp_f32_e32 v55, v55
	v_exp_f32_e32 v56, v56
	v_exp_f32_e32 v57, v57
	v_mfma_f32_32x32x16_bf16 v[2:17], v[200:203], v[186:189], v[2:17]
	ds_read_b64_tr_b16 v[186:187],v153 offset:3072
	ds_read_b64_tr_b16 v[188:189],v153 offset:3584
	v_exp_f32_e32 v58, v58
	v_exp_f32_e32 v59, v59
	v_exp_f32_e32 v60, v60
	v_exp_f32_e32 v61, v61
	v_mfma_f32_32x32x16_bf16 v[18:33], v[200:203], v[192:195], v[18:33]
	ds_read_b64_tr_b16 v[192:193],v153 offset:7168
	ds_read_b64_tr_b16 v[194:195],v153 offset:7680
	v_exp_f32_e32 v62, v62
	v_exp_f32_e32 v63, v63
	v_exp_f32_e32 v64, v64
	v_exp_f32_e32 v65, v65
	v_cvt_pk_bf16_f32 v204, v50, v51
	v_cvt_pk_bf16_f32 v205, v52, v53
	v_cvt_pk_bf16_f32 v206, v54, v55
	v_cvt_pk_bf16_f32 v207, v56, v57
	v_cvt_pk_bf16_f32 v208, v58, v59
	v_cvt_pk_bf16_f32 v209, v60, v61
	v_cvt_pk_bf16_f32 v210, v62, v63
	v_cvt_pk_bf16_f32 v211, v64, v65
	v_pk_add_f32 v[212:213], v[50:51], v[212:213]
	v_pk_add_f32 v[212:213], v[52:53], v[212:213]
	v_pk_add_f32 v[212:213], v[54:55], v[212:213]
	v_pk_add_f32 v[212:213], v[56:57], v[212:213]
	v_pk_add_f32 v[212:213], v[58:59], v[212:213]
	v_pk_add_f32 v[212:213], v[60:61], v[212:213]
	v_pk_add_f32 v[212:213], v[62:63], v[212:213]
	v_pk_add_f32 v[212:213], v[64:65], v[212:213]
	v_add_f32_e32 v212, v212, v213
	v_cmp_lt_f32_e32 vcc, s61, v212
	v_add_f32_e32 v119, v119, v212
	s_waitcnt lgkmcnt(6)
	v_mfma_f32_32x32x16_bf16 v[2:17], v[204:207], v[178:181], v[2:17]
	v_lshrrev_b32_e32 v34, v152, v140
	v_xor_b32_e32 v177, 0x80000000, v113
	v_bfe_i32 v49, v34, 27, 1
	v_bfe_i32 v48, v34, 26, 1
	v_bfe_i32 v47, v34, 25, 1
	v_bfe_i32 v46, v34, 24, 1
	v_bfe_i32 v45, v34, 19, 1
	v_bfe_i32 v44, v34, 18, 1
	v_bfe_i32 v43, v34, 17, 1
	s_waitcnt lgkmcnt(4)
	v_mfma_f32_32x32x16_bf16 v[18:33], v[204:207], v[182:185], v[18:33]
	v_bfe_i32 v42, v34, 16, 1
	v_bfe_i32 v41, v34, 11, 1
	v_bfe_i32 v40, v34, 10, 1
	v_bfe_i32 v39, v34, 9, 1
	v_bfe_i32 v38, v34, 8, 1
	v_bfe_i32 v37, v34, 3, 1
	v_bfe_i32 v36, v34, 2, 1
	v_bfe_i32 v35, v34, 1, 1
	v_bfe_i32 v34, v34, 0, 1
	s_waitcnt lgkmcnt(2)
	v_mfma_f32_32x32x16_bf16 v[2:17], v[208:211], v[186:189], v[2:17]
	v_bfi_b32 v49, v49, v177, v245
	v_bfi_b32 v48, v48, v177, v245
	v_bfi_b32 v47, v47, v177, v245
	v_bfi_b32 v46, v46, v177, v245
	v_bfi_b32 v45, v45, v177, v245
	v_bfi_b32 v44, v44, v177, v245
	v_bfi_b32 v43, v43, v177, v245
	v_bfi_b32 v42, v42, v177, v245
	v_bfi_b32 v41, v41, v177, v245
	s_waitcnt lgkmcnt(0)
	v_mfma_f32_32x32x16_bf16 v[18:33], v[208:211], v[192:195], v[18:33]
	v_bfi_b32 v40, v40, v177, v245
	v_bfi_b32 v39, v39, v177, v245
	v_bfi_b32 v38, v38, v177, v245
	v_bfi_b32 v37, v37, v177, v245
	v_bfi_b32 v36, v36, v177, v245
	v_bfi_b32 v35, v35, v177, v245
	v_bfi_b32 v34, v34, v177, v245
	v_lshrrev_b32_e32 v50, v152, v141
	s_cbranch_vccz .LBB0_1074
	v_and_b32_e32 v192, 64, v240
	v_xor_b32_e32 v213, 32, v240
	v_add_u32_e32 v192, 64, v192
	v_cmp_lt_i32_e32 vcc, v213, v192
	s_nop 1
	v_cndmask_b32_e32 v213, v240, v213, vcc
	v_lshlrev_b32_e32 v213, 2, v213
	ds_bpermute_b32 v213, v213, v212
	v_max_f32_e32 v212, v212, v212
	s_waitcnt lgkmcnt(0)
	v_max_f32_e32 v213, v213, v213
	v_max_f32_e32 v212, v212, v213
	v_log_f32_e32 v213, v212
	v_cmp_lt_f32_e32 vcc, s61, v212
	v_floor_f32_e32 v213, v213
	s_nop 0
	v_cndmask_b32_e32 v212, 0, v213, vcc
	v_exp_f32_e64 v213, -v212
	s_and_saveexec_b64 s[18:19], s[12:13]
	ds_write_b32 v115, v213 offset:32768
	s_or_b64 exec, exec, s[18:19]
	s_waitcnt lgkmcnt(0)
	v_add_f32_e32 v113, v113, v212
	v_mul_f32_e32 v119, v119, v213
	ds_read_b128 v[192:195], v111 offset:32768
	ds_read_b128 v[196:199], v111 offset:32800
	ds_read_b128 v[200:203], v111 offset:32832
	ds_read_b128 v[204:207], v111 offset:32864
	v_xor_b32_e32 v177, 0x80000000, v113
	v_sub_f32_e32 v34, v34, v212
	v_sub_f32_e32 v35, v35, v212
	v_sub_f32_e32 v36, v36, v212
	v_sub_f32_e32 v37, v37, v212
	v_sub_f32_e32 v38, v38, v212
	v_sub_f32_e32 v39, v39, v212
	v_sub_f32_e32 v40, v40, v212
	v_sub_f32_e32 v41, v41, v212
	v_sub_f32_e32 v42, v42, v212
	v_sub_f32_e32 v43, v43, v212
	v_sub_f32_e32 v44, v44, v212
	v_sub_f32_e32 v45, v45, v212
	v_sub_f32_e32 v46, v46, v212
	v_sub_f32_e32 v47, v47, v212
	v_sub_f32_e32 v48, v48, v212
	v_sub_f32_e32 v49, v49, v212
	s_waitcnt lgkmcnt(3)
	v_pk_mul_f32 v[4:5], v[4:5], v[194:195]
	s_waitcnt lgkmcnt(2)
	v_pk_mul_f32 v[8:9], v[8:9], v[198:199]
	s_waitcnt lgkmcnt(1)
	v_pk_mul_f32 v[12:13], v[12:13], v[202:203]
	s_waitcnt lgkmcnt(0)
	v_pk_mul_f32 v[16:17], v[16:17], v[206:207]
	v_pk_mul_f32 v[14:15], v[14:15], v[204:205]
	v_pk_mul_f32 v[10:11], v[10:11], v[200:201]
	v_pk_mul_f32 v[6:7], v[6:7], v[196:197]
	v_pk_mul_f32 v[2:3], v[2:3], v[192:193]
	v_pk_mul_f32 v[32:33], v[32:33], v[206:207]
	v_pk_mul_f32 v[28:29], v[28:29], v[202:203]
	v_pk_mul_f32 v[24:25], v[24:25], v[198:199]
	v_pk_mul_f32 v[20:21], v[20:21], v[194:195]
	v_pk_mul_f32 v[30:31], v[30:31], v[204:205]
	v_pk_mul_f32 v[26:27], v[26:27], v[200:201]
	v_pk_mul_f32 v[22:23], v[22:23], v[196:197]
	v_pk_mul_f32 v[18:19], v[18:19], v[192:193]
.LBB0_1074:
.LBB0_1076:
	s_cmp_ge_u32 s25, s26
	s_waitcnt lgkmcnt(0)
	s_barrier
	ds_read_b128 v[178:181], v176 offset:16384
	ds_read_b128 v[182:185], v176 offset:18432
	ds_read_b128 v[186:189], v176 offset:20480
	ds_read_b128 v[192:195], v176 offset:22528
	ds_read_b128 v[196:199], v176 offset:16896
	ds_read_b128 v[200:203], v176 offset:18944
	ds_read_b128 v[204:207], v176 offset:20992
	ds_read_b128 v[208:211], v176 offset:23040
	s_cbranch_scc1 .LBB0_1078
	global_load_dwordx4 v[90:93], v146, s[46:47]
	global_load_dwordx4 v[94:97], v144, s[48:49]
	global_load_dwordx2 v[140:141], v142, s[50:51]
	s_add_u32 s46, s46, 0x8000
	s_addc_u32 s47, s47, 0
	s_add_u32 s48, s48, 0x8000
	s_addc_u32 s49, s49, 0
	s_add_u32 s50, s50, 0x8000
	s_addc_u32 s51, s51, 0

; #define LAS __attribute__((address_space(3)))
; __device__ __forceinline__ void attn_unit(const AttArgs& a, int b, int h, int qb, LAS unsigned char* shm, int tid) {
;     ...
;     for (int t2 = 0; t2 < NT; t2 += 2) {
; #pragma unroll
;       for (int par = 0; par < 2; ++par) { const int t = t2 + par;
;         LAS unsigned char* Kb = shm + AT_KV + par * 16384; LAS unsigned char* Vb = Kb + 8192; const u64 mw = mwr[par];
;         if (t + 2 < NT) { kr[par] = *(const u32x4_t*)(ksrc + (size_t)(t + 2) * 64 * 256); vr[par] = *(const u32x4_t*)(vsrc + (size_t)(t + 2) * 64 * 256); mwr[par] = mrow[(size_t)(t + 2) * SEQ]; }
;     ...
;         if (t + 1 < NT) { LAS unsigned char* Kn = shm + AT_KV + (par ^ 1) * 16384; *(LAS u32x4_t*)(Kn + wave * 1024 + lane * 16) = kr[par ^ 1]; *(LAS u32x4_t*)(Kn + 8192 + wave * 1024 + lane * 16) = vr[par ^ 1]; }
;         __syncthreads();
;       }
;     }
.LBB0_1082:
.LBB0_1084:
	s_add_u32 s14, s14, 0x10000
	s_addc_u32 s15, s15, 0
	s_add_i32 s25, s25, 2
	s_cmp_ge_u32 s27, s26
	s_waitcnt lgkmcnt(0)
	s_barrier
	s_cbranch_scc1 .LBB0_1086
	s_branch .LBB0_1066
